# v18 + R2X: retention-output unit issues its state/q/k/v loads before the decay log-sigmoid math
# speedup vs baseline: 1.0044x; 1.0029x over previous
; #define LAS __attribute__((address_space(3)))
; __device__ __forceinline__ unsigned f2bf(float f) { unsigned u = __builtin_bit_cast(unsigned, f); return (u + 0x7fffu + ((u >> 16) & 1u)) >> 16; }
; __device__ __forceinline__ float log_sigmoid(float x) { return fminf(x, 0.f) - log1pf(expf(-fabsf(x))); }
; __device__ __forceinline__ void ret_out_unit(int unit, const bf16* RQ, const bf16* RK, const bf16* RV, const bf16* RG, const float* decay_l, const float* RETC, bf16* MIX, lds_t* lds, int tid, int lane, int wave) {
;     ...
;     const float lgf = log_sigmoid(decay_l[h]), lgb = log_sigmoid(decay_l[4 + h]);
;     v4u gpre[2]; { const v4u* gp0 = (const v4u*)(RG + (size_t)(m0 + (tid >> 2)) * 256 + h * 64 + (tid & 3) * 16); gpre[0] = gp0[0]; gpre[1] = gp0[1]; }
;     { const float* base = RETC + ((size_t)bh * 34 + c) * 2 * 4096 + tid * 8;
;         const f32x4 sf0 = *(const f32x4*)base, sf1 = *(const f32x4*)(base + 4), sb0 = *(const f32x4*)(base + 4096), sb1 = *(const f32x4*)(base + 4096 + 4);
;         const int d = tid >> 3, v0 = (tid & 7) * 8;
; #pragma unroll
;         for (int e = 0; e < 4; ++e) { *(LAS unsigned short*)(Sft + (v0 + e) * RT_LDD + d * 2) = (unsigned short)f2bf(sf0[e]); *(LAS unsigned short*)(Sft + (v0 + 4 + e) * RT_LDD + d * 2) = (unsigned short)f2bf(sf1[e]);
;             *(LAS unsigned short*)(Sbt + (v0 + e) * RT_LDD + d * 2) = (unsigned short)f2bf(sb0[e]); *(LAS unsigned short*)(Sbt + (v0 + 4 + e) * RT_LDD + d * 2) = (unsigned short)f2bf(sb1[e]); } }
;     { const int j = tid >> 2, d0 = (tid & 3) * 16; const size_t go = (size_t)(m0 + j) * 256 + h * 64 + d0;
;         const v4u* qp = (const v4u*)(RQ + go); const v4u* kp = (const v4u*)(RK + go); const v4u* vp = (const v4u*)(RV + go);
; #pragma unroll
;         for (int q = 0; q < 2; ++q) { *(LAS v4u*)(Qs + j * RT_LDD + (d0 + 8 * q) * 2) = qp[q]; *(LAS v4u*)(Ks + j * RT_LDD + (d0 + 8 * q) * 2) = kp[q]; const v4u vw = vp[q];
.LBB0_777:
	s_and_b32 s0, s10, 3
	s_lshl_b32 s13, s0, 2
	v_mov_b32_e32 v2, s13
	global_load_dword v25, v2, s[82:83]
	global_load_dword v24, v2, s[82:83] offset:16
	s_lshl_b32 s84, s0, 7
	s_mul_hi_i32 s1, s10, 34
	s_ashr_i32 s10, s11, 31
	s_add_u32 s0, s12, s11
	s_addc_u32 s1, s1, s10
	s_lshl_b64 s[0:1], s[0:1], 15
	v_lshl_add_u64 v[14:15], v[58:59], 0, s[0:1]
	s_mov_b32 s0, 0xbfb8aa3b
	s_mov_b32 s1, 0xb2a5705f
	s_mov_b32 s10, 0x42ce8ed0
	s_mov_b32 s11, 0x33800000
	s_mov_b64 s[12:13], 0x4000
	v_add_u32_e32 v60, s9, v62
	v_ashrrev_i32_e32 v61, 31, v60
	global_load_dwordx4 v[180:183], v[14:15], off offset:16
	global_load_dwordx4 v[184:187], v[14:15], off
	v_lshl_add_u64 v[192:193], v[14:15], 0, s[12:13]
	global_load_dwordx4 v[188:191], v[192:193], off
	global_load_dwordx4 v[192:195], v[192:193], off offset:16
	v_lshlrev_b64 v[242:243], 9, v[60:61]
	v_readlane_b32 s98, v255, 3
	v_readlane_b32 s99, v255, 4
	v_or3_b32 v242, s84, v0, v242
	v_readlane_b32 s100, v252, 30
	v_readlane_b32 s101, v252, 31
	v_lshl_add_u64 v[206:207], s[98:99], 0, v[242:243]
	v_readlane_b32 s98, v252, 32
	v_readlane_b32 s99, v252, 33
	v_lshl_add_u64 v[230:231], s[100:101], 0, v[242:243]
	global_load_dwordx4 v[202:205], v[206:207], off offset:16
	global_load_dwordx4 v[206:209], v[206:207], off
	v_lshl_add_u64 v[238:239], s[98:99], 0, v[242:243]
	global_load_dwordx4 v[226:229], v[230:231], off offset:16
	global_load_dwordx4 v[230:233], v[230:231], off
	global_load_dwordx4 v[234:237], v[238:239], off
	global_load_dwordx4 v[238:241], v[238:239], off offset:16
	s_waitcnt vmcnt(11)
	v_mul_f32_e64 v2, |v25|, s0
	v_fma_f32 v3, |v25|, s0, -v2
	v_rndne_f32_e32 v4, v2
	v_fma_f32 v3, |v25|, s1, v3
	v_sub_f32_e32 v2, v2, v4
	v_add_f32_e32 v2, v2, v3
	v_cvt_i32_f32_e32 v4, v4
	v_exp_f32_e32 v2, v2
	s_waitcnt vmcnt(10)
	v_mul_f32_e64 v3, |v24|, s0
	v_rndne_f32_e32 v5, v3
	v_cmp_ngt_f32_e64 vcc, |v25|, s10
	v_ldexp_f32 v2, v2, v4
	v_fma_f32 v4, |v24|, s0, -v3
	v_fma_f32 v4, |v24|, s1, v4
	v_sub_f32_e32 v3, v3, v5
	v_add_f32_e32 v3, v3, v4
	v_cvt_i32_f32_e32 v5, v5
	v_exp_f32_e32 v3, v3
	v_cndmask_b32_e32 v2, 0, v2, vcc
	v_cmp_ngt_f32_e64 vcc, |v24|, s10
	s_mov_b32 s0, 0xc2b17218
	v_ldexp_f32 v3, v3, v5
	v_cndmask_b32_e32 v3, 0, v3, vcc
	v_cmp_nlt_f32_e64 vcc, |v25|, s0
	s_mov_b32 s1, 0x3f317218
	s_mov_b32 s10, 0x7f800000
	v_cndmask_b32_e32 v4, v219, v2, vcc
	v_cmp_nlt_f32_e64 vcc, |v24|, s0
	v_add_f32_e32 v5, 1.0, v4
	v_frexp_mant_f32_e32 v6, v5
	v_cndmask_b32_e32 v26, v219, v3, vcc
	v_cvt_f64_f32_e32 v[2:3], v5
	s_mov_b32 s0, 0x3f2aaaab
	v_frexp_exp_i32_f64_e32 v2, v[2:3]
	v_cmp_gt_f32_e32 vcc, s0, v6
	v_add_f32_e32 v7, 1.0, v26
	v_frexp_mant_f32_e32 v8, v7
	v_subbrev_co_u32_e32 v6, vcc, 0, v2, vcc
	v_cvt_f64_f32_e32 v[2:3], v7
	v_frexp_exp_i32_f64_e32 v2, v[2:3]
	v_cmp_gt_f32_e32 vcc, s0, v8
	s_movk_i32 s0, 0x4000
	s_nop 0
	v_subbrev_co_u32_e32 v18, vcc, 0, v2, vcc
	v_add_f32_e32 v2, -1.0, v5
	v_sub_f32_e32 v3, v2, v5
	v_sub_f32_e32 v2, v4, v2
	v_add_f32_e32 v3, 1.0, v3
	v_add_f32_e32 v2, v2, v3
	v_sub_u32_e32 v3, 0, v6
	v_cvt_f32_i32_e32 v6, v6
	v_ldexp_f32 v5, v5, v3
	v_ldexp_f32 v2, v2, v3
	v_add_f32_e32 v3, -1.0, v5
	v_add_f32_e32 v8, 1.0, v5
	v_add_f32_e32 v9, 1.0, v3
	v_add_f32_e32 v10, -1.0, v8
	v_sub_f32_e32 v9, v5, v9
	v_sub_f32_e32 v5, v5, v10
	v_mul_f32_e32 v10, 0x3f317218, v6
	v_add_f32_e32 v9, v2, v9
	v_add_f32_e32 v2, v2, v5
	v_fma_f32 v5, v6, s1, -v10
	v_add_f32_e32 v12, v8, v2
	v_fmac_f32_e32 v5, 0xb102e308, v6
	v_sub_f32_e32 v6, v8, v12
	v_rcp_f32_e32 v8, v12
	v_add_f32_e32 v13, v10, v5
	v_add_f32_e32 v11, v3, v9
	v_add_f32_e32 v2, v2, v6
	v_sub_f32_e32 v6, v13, v10
	v_sub_f32_e32 v3, v3, v11
	v_sub_f32_e32 v5, v5, v6
	v_mul_f32_e32 v6, v11, v8
	v_add_f32_e32 v3, v9, v3
	v_mul_f32_e32 v9, v12, v6
	v_fma_f32 v10, v6, v12, -v9
	v_fmac_f32_e32 v10, v6, v2
	v_add_f32_e32 v16, v9, v10
	v_sub_f32_e32 v17, v11, v16
	v_sub_f32_e32 v9, v16, v9
	v_sub_f32_e32 v11, v11, v17
	v_sub_f32_e32 v9, v9, v10
	v_sub_f32_e32 v10, v11, v16
	v_add_f32_e32 v3, v3, v10
	v_add_f32_e32 v3, v9, v3
	v_add_f32_e32 v9, v17, v3
	v_mul_f32_e32 v10, v8, v9
	v_sub_f32_e32 v11, v17, v9
	v_mul_f32_e32 v16, v12, v10
	v_add_f32_e32 v3, v3, v11
	v_add_f32_e32 v11, v6, v10
	v_fma_f32 v12, v10, v12, -v16
	v_sub_f32_e32 v6, v11, v6
	v_fmac_f32_e32 v12, v10, v2
	v_sub_f32_e32 v2, v10, v6
	v_add_f32_e32 v6, v16, v12
	v_sub_f32_e32 v10, v6, v16
	v_sub_f32_e32 v16, v9, v6
	v_sub_f32_e32 v9, v9, v16
	v_sub_f32_e32 v6, v9, v6
	v_sub_f32_e32 v10, v10, v12
	v_add_f32_e32 v3, v3, v6
	v_add_f32_e32 v3, v10, v3
	v_add_f32_e32 v3, v16, v3
	v_mul_f32_e32 v3, v8, v3
	v_add_f32_e32 v2, v2, v3
	v_add_f32_e32 v3, v11, v2
	v_mul_f32_e32 v6, v3, v3
	v_fmamk_f32 v10, v6, 0x3e9b6dac, v217
	v_sub_f32_e32 v8, v3, v11
	v_ldexp_f32 v9, v3, 1
	v_mul_f32_e32 v3, v3, v6
	v_fmaak_f32 v6, v6, v10, 0x3f2aaada
	v_mul_f32_e32 v3, v3, v6
	v_add_f32_e32 v6, v9, v3
	v_sub_f32_e32 v2, v2, v8
	v_sub_f32_e32 v8, v6, v9
	v_ldexp_f32 v2, v2, 1
	v_sub_f32_e32 v3, v3, v8
	v_add_f32_e32 v2, v2, v3
	v_add_f32_e32 v3, v6, v2
	v_sub_f32_e32 v6, v3, v6
	v_add_f32_e32 v8, v13, v3
	v_sub_f32_e32 v2, v2, v6
	v_sub_f32_e32 v6, v8, v13
	v_sub_f32_e32 v9, v8, v6
	v_sub_f32_e32 v3, v3, v6
	v_add_f32_e32 v6, v5, v2
	v_sub_f32_e32 v9, v13, v9
	v_sub_f32_e32 v10, v6, v5
	v_add_f32_e32 v3, v3, v9
	v_sub_f32_e32 v9, v6, v10
	v_sub_f32_e32 v2, v2, v10
	v_sub_f32_e32 v5, v5, v9
	v_add_f32_e32 v3, v6, v3
	v_add_f32_e32 v2, v2, v5
	v_add_f32_e32 v5, v8, v3
	v_sub_f32_e32 v6, v5, v8
	v_sub_f32_e32 v3, v3, v6
	v_add_f32_e32 v2, v2, v3
	v_add_f32_e32 v2, v5, v2
	v_cmp_neq_f32_e32 vcc, s10, v4
	s_nop 1
	v_cndmask_b32_e32 v2, v219, v2, vcc
	v_cmp_lt_f32_e64 vcc, |v4|, s11
; #define LAS __attribute__((address_space(3)))
; __device__ __forceinline__ unsigned f2bf(float f) { unsigned u = __builtin_bit_cast(unsigned, f); return (u + 0x7fffu + ((u >> 16) & 1u)) >> 16; }
; __device__ __forceinline__ float log_sigmoid(float x) { return fminf(x, 0.f) - log1pf(expf(-fabsf(x))); }
; __device__ __forceinline__ void ret_out_unit(int unit, const bf16* RQ, const bf16* RK, const bf16* RV, const bf16* RG, const float* decay_l, const float* RETC, bf16* MIX, lds_t* lds, int tid, int lane, int wave) {
;     ...
;     const float lgf = log_sigmoid(decay_l[h]), lgb = log_sigmoid(decay_l[4 + h]);
;     v4u gpre[2]; { const v4u* gp0 = (const v4u*)(RG + (size_t)(m0 + (tid >> 2)) * 256 + h * 64 + (tid & 3) * 16); gpre[0] = gp0[0]; gpre[1] = gp0[1]; }
;     { const float* base = RETC + ((size_t)bh * 34 + c) * 2 * 4096 + tid * 8;
;         const f32x4 sf0 = *(const f32x4*)base, sf1 = *(const f32x4*)(base + 4), sb0 = *(const f32x4*)(base + 4096), sb1 = *(const f32x4*)(base + 4096 + 4);
;         const int d = tid >> 3, v0 = (tid & 7) * 8;
; #pragma unroll
;         for (int e = 0; e < 4; ++e) { *(LAS unsigned short*)(Sft + (v0 + e) * RT_LDD + d * 2) = (unsigned short)f2bf(sf0[e]); *(LAS unsigned short*)(Sft + (v0 + 4 + e) * RT_LDD + d * 2) = (unsigned short)f2bf(sf1[e]);
;             *(LAS unsigned short*)(Sbt + (v0 + e) * RT_LDD + d * 2) = (unsigned short)f2bf(sb0[e]); *(LAS unsigned short*)(Sbt + (v0 + 4 + e) * RT_LDD + d * 2) = (unsigned short)f2bf(sb1[e]); } }
;     { const int j = tid >> 2, d0 = (tid & 3) * 16; const size_t go = (size_t)(m0 + j) * 256 + h * 64 + d0;
;         const v4u* qp = (const v4u*)(RQ + go); const v4u* kp = (const v4u*)(RK + go); const v4u* vp = (const v4u*)(RV + go);
; #pragma unroll
;         for (int q = 0; q < 2; ++q) { *(LAS v4u*)(Qs + j * RT_LDD + (d0 + 8 * q) * 2) = qp[q]; *(LAS v4u*)(Ks + j * RT_LDD + (d0 + 8 * q) * 2) = kp[q]; const v4u vw = vp[q];
; #pragma unroll
;             for (int e = 0; e < 4; ++e) { const unsigned vv = vw[e]; const int d = d0 + q * 8 + 2 * e;
;                 *(LAS unsigned short*)(Vt + d * RT_LDK + j * 2) = (unsigned short)(vv & 0xffffu); *(LAS unsigned short*)(Vt + (d + 1) * RT_LDK + j * 2) = (unsigned short)(vv >> 16); } } }
	s_nop 1
	v_cndmask_b32_e32 v27, v2, v4, vcc
	v_add_f32_e32 v2, -1.0, v7
	v_sub_f32_e32 v3, v2, v7
	v_add_f32_e32 v3, 1.0, v3
	v_sub_f32_e32 v2, v26, v2
	v_add_f32_e32 v2, v2, v3
	v_sub_u32_e32 v3, 0, v18
	v_ldexp_f32 v4, v7, v3
	v_ldexp_f32 v2, v2, v3
	v_add_f32_e32 v3, -1.0, v4
	v_add_f32_e32 v7, 1.0, v4
	v_add_f32_e32 v5, 1.0, v3
	v_add_f32_e32 v8, -1.0, v7
	v_sub_f32_e32 v5, v4, v5
	v_sub_f32_e32 v4, v4, v8
	v_add_f32_e32 v5, v2, v5
	v_add_f32_e32 v2, v2, v4
	v_add_f32_e32 v19, v7, v2
	v_rcp_f32_e32 v20, v19
	v_add_f32_e32 v6, v3, v5
	v_sub_f32_e32 v3, v3, v6
	v_add_f32_e32 v12, v5, v3
	v_sub_f32_e32 v3, v7, v19
	v_mul_f32_e32 v22, v6, v20
	v_add_f32_e32 v21, v2, v3
	v_mul_f32_e32 v2, v19, v22
	v_fma_f32 v13, v22, v19, -v2
	v_fmac_f32_e32 v13, v22, v21
	v_add_f32_e32 v16, v2, v13
	v_sub_f32_e32 v23, v6, v16
	v_sub_f32_e32 v17, v16, v2
	v_sub_f32_e32 v28, v6, v23
	v_sub_f32_e32 v16, v28, v16
	v_add_f32_e32 v12, v12, v16
	v_sub_f32_e32 v13, v17, v13
	v_add_f32_e32 v28, v13, v12
	v_add_f32_e32 v29, v23, v28
	v_mul_f32_e32 v30, v20, v29
	v_mul_f32_e32 v31, v19, v30
	v_fma_f32 v19, v30, v19, -v31
	v_fmac_f32_e32 v19, v30, v21
	v_sub_f32_e32 v21, v23, v29
	v_add_f32_e32 v23, v31, v19
	v_add_f32_e32 v21, v28, v21
	v_sub_f32_e32 v28, v23, v31
	v_sub_f32_e32 v31, v29, v23
	v_sub_f32_e32 v29, v29, v31
	v_sub_f32_e32 v23, v29, v23
	v_add_f32_e32 v21, v21, v23
	v_sub_f32_e32 v19, v28, v19
	v_add_f32_e32 v19, v19, v21
	v_add_f32_e32 v19, v31, v19
	v_cvt_f32_i32_e32 v18, v18
	v_mul_f32_e32 v19, v20, v19
	v_add_f32_e32 v20, v22, v30
	v_sub_f32_e32 v21, v20, v22
	v_sub_f32_e32 v21, v30, v21
	v_add_f32_e32 v19, v21, v19
	v_mul_f32_e32 v51, 0x3f317218, v18
	v_add_f32_e32 v48, v20, v19
	v_fma_f32 v52, v18, s1, -v51
	v_fmac_f32_e32 v52, 0xb102e308, v18
	v_sub_f32_e32 v18, v48, v20
	v_readlane_b32 s0, v252, 34
	v_sub_f32_e32 v53, v19, v18
	v_lshlrev_b64 v[18:19], 9, v[60:61]
	v_readlane_b32 s1, v252, 35
	v_mul_f32_e32 v49, v48, v48
	v_fmamk_f32 v21, v49, 0x3e9b6dac, v217
	v_lshl_add_u64 v[22:23], s[0:1], 0, v[18:19]
	v_fmaak_f32 v50, v49, v21, 0x3f2aaada
	v_add_f32_e32 v54, v51, v52
	v_lshl_add_u64 v[22:23], v[22:23], 0, s[84:85]
	v_lshl_add_u64 v[22:23], v[22:23], 0, v[0:1]
	v_cmp_neq_f32_e32 vcc, s10, v26
	s_nop 0
	s_nop 0
	s_nop 0
	v_sub_f32_e32 v20, v54, v51
	v_mul_f32_e32 v21, v48, v49
	v_sub_f32_e32 v178, v52, v20
	v_ldexp_f32 v20, v48, 1
	v_mul_f32_e32 v48, v21, v50
	v_add_f32_e32 v49, v20, v48
	v_sub_f32_e32 v50, v49, v20
	v_ldexp_f32 v51, v53, 1
	v_sub_f32_e32 v48, v48, v50
	v_add_f32_e32 v48, v51, v48
	v_add_f32_e32 v50, v49, v48
	v_sub_f32_e32 v49, v50, v49
	v_sub_f32_e32 v48, v48, v49
	v_add_f32_e32 v49, v54, v50
	v_sub_f32_e32 v51, v49, v54
	v_sub_f32_e32 v52, v49, v51
	v_sub_f32_e32 v52, v54, v52
	v_sub_f32_e32 v50, v50, v51
	v_add_f32_e32 v179, v50, v52
	global_load_dwordx4 v[50:53], v[22:23], off offset:16
	global_load_dwordx4 v[54:57], v[22:23], off
	s_waitcnt vmcnt(10)
	v_bfe_u32 v22, v184, 16, 1
	v_add3_u32 v6, v184, v22, s33
	ds_write_b16_d16_hi v160, v6 offset:54272
	v_bfe_u32 v6, v180, 16, 1
	v_add3_u32 v2, v180, v6, s33
	ds_write_b16_d16_hi v160, v2 offset:54848
	s_waitcnt vmcnt(9)
	v_bfe_u32 v2, v188, 16, 1
	v_add3_u32 v2, v188, v2, s33
	ds_write_b16_d16_hi v160, v2 offset:63488
	s_waitcnt vmcnt(8)
	v_bfe_u32 v2, v192, 16, 1
	v_add3_u32 v2, v192, v2, s33
	ds_write_b16_d16_hi v160, v2 offset:64064
	v_bfe_u32 v2, v185, 16, 1
	v_add3_u32 v2, v185, v2, s33
	ds_write_b16_d16_hi v160, v2 offset:54416
	v_bfe_u32 v2, v181, 16, 1
	v_add3_u32 v2, v181, v2, s33
	ds_write_b16_d16_hi v160, v2 offset:54992
	v_bfe_u32 v2, v189, 16, 1
	v_add3_u32 v2, v189, v2, s33
	ds_write_b16_d16_hi v160, v2 offset:63632
	v_bfe_u32 v2, v193, 16, 1
	v_add3_u32 v2, v193, v2, s33
	ds_write_b16_d16_hi v160, v2 offset:64208
	v_bfe_u32 v2, v186, 16, 1
	v_add3_u32 v2, v186, v2, s33
	ds_write_b16_d16_hi v160, v2 offset:54560
	v_bfe_u32 v2, v182, 16, 1
	v_add3_u32 v2, v182, v2, s33
	ds_write_b16_d16_hi v160, v2 offset:55136
	v_bfe_u32 v2, v190, 16, 1
	v_add3_u32 v2, v190, v2, s33
	ds_write_b16_d16_hi v160, v2 offset:63776
	v_bfe_u32 v2, v194, 16, 1
	v_add3_u32 v2, v194, v2, s33
	ds_write_b16_d16_hi v160, v2 offset:64352
	v_bfe_u32 v2, v187, 16, 1
	v_add3_u32 v2, v187, v2, s33
	ds_write_b16_d16_hi v160, v2 offset:54704
	v_bfe_u32 v2, v183, 16, 1
	v_add3_u32 v2, v183, v2, s33
	ds_write_b16_d16_hi v160, v2 offset:55280
	v_bfe_u32 v2, v191, 16, 1
	v_add3_u32 v2, v191, v2, s33
	ds_write_b16_d16_hi v160, v2 offset:63920
	v_bfe_u32 v2, v195, 16, 1
	v_add3_u32 v2, v195, v2, s33
	ds_write_b16_d16_hi v160, v2 offset:64496
	v_add_u32_e32 v2, v63, v64
	s_waitcnt vmcnt(6)
	ds_write_b128 v2, v[206:209]
	s_waitcnt vmcnt(4)
	ds_write_b128 v2, v[230:233] offset:18432
	s_waitcnt vmcnt(3)
	ds_write_b16 v161, v234 offset:36864
	ds_write_b16_d16_hi v161, v234 offset:37136
	ds_write_b16 v161, v235 offset:37408
	ds_write_b16_d16_hi v161, v235 offset:37680
	ds_write_b16 v161, v236 offset:37952
	ds_write_b16_d16_hi v161, v236 offset:38224
	ds_write_b16 v161, v237 offset:38496
	ds_write_b16_d16_hi v161, v237 offset:38768
	ds_write_b128 v162, v[202:205]
	ds_write_b128 v162, v[226:229] offset:18432
	s_waitcnt vmcnt(2)
	ds_write_b16 v161, v238 offset:39040
	ds_write_b16_d16_hi v161, v238 offset:39312
	ds_write_b16 v161, v239 offset:39584
	ds_write_b16_d16_hi v161, v239 offset:39856
	ds_write_b16 v161, v240 offset:40128
	ds_write_b16_d16_hi v161, v240 offset:40400
	ds_write_b16 v161, v241 offset:40672
	ds_write_b16_d16_hi v161, v241 offset:40944
	s_waitcnt lgkmcnt(0)
	s_barrier
; #define LAS __attribute__((address_space(3)))
; __device__ __forceinline__ unsigned f2bf(float f) { unsigned u = __builtin_bit_cast(unsigned, f); return (u + 0x7fffu + ((u >> 16) & 1u)) >> 16; }
; __device__ __forceinline__ int crow16(int r, int hi) { return (r & 3) + 8 * (r >> 2) + 4 * hi; }
; __device__ __forceinline__ void ret_out_unit(int unit, const bf16* RQ, const bf16* RK, const bf16* RV, const bf16* RG, const float* decay_l, const float* RETC, bf16* MIX, lds_t* lds, int tid, int lane, int wave) {
;     ...
; #pragma unroll
;     for (int tt = 0; tt < 2; ++tt) { const int tile = wave * 2 + tt, it = tile >> 2, jt = tile & 3; f32x16 acc = {};
;         mma32<4>(acc, Qs + 32 * it * RT_LDD, RT_LDD, Ks + 32 * jt * RT_LDD, RT_LDD, lane);
;         const int j = 32 * jt + (lane & 31);
; #pragma unroll
;         for (int r = 0; r < 16; ++r) { const int i = 32 * it + crow16(r, lane >> 5); const float dd = (float)(i - j); const float w = acc[r] * __expf(dd >= 0.f ? lgf * dd : -lgb * dd);
;             *(LAS unsigned short*)(Ws + i * RT_LDK + j * 2) = (unsigned short)f2bf(w); } }
	ds_read_b128 v[2:5], v163
	v_add_u32_e32 v32, s63, v65
	ds_read_b128 v[6:9], v32 offset:18432
	v_add_f32_e32 v180, v178, v48
	v_sub_f32_e32 v181, v180, v178
	v_sub_f32_e32 v182, v180, v181
	v_sub_f32_e32 v10, v178, v182
	v_sub_f32_e32 v11, v48, v181
	v_add_f32_e32 v22, v11, v10
	s_waitcnt lgkmcnt(0)
	v_mfma_f32_32x32x16_bf16 v[2:17], v[2:5], v[6:9], 0
	ds_read_b128 v[18:21], v163 offset:32
	ds_read_b128 v[28:31], v32 offset:18464
	v_add_f32_e32 v23, v180, v179
	v_add_f32_e32 v33, v49, v23
	v_sub_f32_e32 v34, v33, v49
	v_sub_f32_e32 v23, v23, v34
	v_add_f32_e32 v22, v22, v23
	v_add_f32_e32 v22, v33, v22
	s_waitcnt lgkmcnt(0)
	v_mfma_f32_32x32x16_bf16 v[2:17], v[18:21], v[28:31], v[2:17]
	ds_read_b128 v[18:21], v163 offset:64
	ds_read_b128 v[28:31], v32 offset:18496
	v_cndmask_b32_e32 v22, v219, v22, vcc
	v_cmp_lt_f32_e64 vcc, |v26|, s11
	v_max_f32_e32 v37, v24, v24
	v_readlane_b32 s0, v253, 47
	v_cndmask_b32_e32 v26, v22, v26, vcc
	s_waitcnt lgkmcnt(0)
	v_mfma_f32_32x32x16_bf16 v[2:17], v[18:21], v[28:31], v[2:17]
	v_max_f32_e32 v22, v25, v25
	v_min_f32_e32 v36, 0, v22
	ds_read_b128 v[22:25], v163 offset:96
	ds_read_b128 v[32:35], v32 offset:18528
	v_min_f32_e32 v18, 0, v37
	v_sub_f32_e32 v179, v36, v27
	v_sub_f32_e32 v178, v18, v26
	v_readlane_b32 s1, v253, 48
	s_waitcnt lgkmcnt(0)
	v_mfma_f32_32x32x16_bf16 v[2:17], v[22:25], v[32:35], v[2:17]
	v_add_u32_e32 v30, s79, v65
	v_cndmask_b32_e64 v18, v179, -v178, s[0:1]
	v_mul_f32_e32 v18, v18, v67
	v_readlane_b32 s0, v253, 49
	v_mul_f32_e32 v18, 0x3fb8aa3b, v18
	v_readlane_b32 s1, v253, 50
	v_exp_f32_e32 v18, v18
	s_nop 0
	v_cndmask_b32_e64 v19, v179, -v178, s[0:1]
	v_mul_f32_e32 v19, v19, v69
	v_mul_f32_e32 v19, 0x3fb8aa3b, v19
	v_exp_f32_e32 v19, v19
	v_mul_f32_e32 v2, v2, v18
	v_bfe_u32 v18, v2, 16, 1
	v_readlane_b32 s0, v253, 51
	v_add3_u32 v2, v2, v18, s33
	v_add_u32_e32 v18, v66, v68
	v_readlane_b32 s1, v253, 52
	ds_write_b16_d16_hi v18, v2
	v_mul_f32_e32 v2, v3, v19
	v_cndmask_b32_e64 v3, v179, -v178, s[0:1]
	v_mul_f32_e32 v3, v3, v70
	v_mul_f32_e32 v3, 0x3fb8aa3b, v3
	v_exp_f32_e32 v3, v3
	v_bfe_u32 v19, v2, 16, 1
	v_readlane_b32 s0, v253, 53
	v_add3_u32 v2, v2, v19, s33
	v_readlane_b32 s1, v253, 54
	ds_write_b16_d16_hi v18, v2 offset:272
	v_mul_f32_e32 v2, v4, v3
	v_cndmask_b32_e64 v3, v179, -v178, s[0:1]
	v_mul_f32_e32 v3, v3, v71
	v_mul_f32_e32 v3, 0x3fb8aa3b, v3
	v_exp_f32_e32 v3, v3
	v_bfe_u32 v4, v2, 16, 1
	v_readlane_b32 s0, v253, 55
	v_add3_u32 v2, v2, v4, s33
	v_readlane_b32 s1, v253, 56
	ds_write_b16_d16_hi v18, v2 offset:544
	v_mul_f32_e32 v2, v5, v3
	v_cndmask_b32_e64 v4, v179, -v178, s[0:1]
	v_bfe_u32 v3, v2, 16, 1
	v_mul_f32_e32 v4, v4, v73
	v_mul_f32_e32 v4, 0x3fb8aa3b, v4
	v_add3_u32 v2, v2, v3, s33
	v_add_u32_e32 v3, v66, v72
	v_exp_f32_e32 v4, v4
	ds_write_b16_d16_hi v3, v2
	v_cndmask_b32_e64 v3, v179, -v178, s[16:17]
	v_mul_f32_e32 v3, v3, v74
	v_mul_f32_e32 v3, 0x3fb8aa3b, v3
	v_exp_f32_e32 v3, v3
	v_mul_f32_e32 v2, v6, v4
	v_bfe_u32 v4, v2, 16, 1
	v_add3_u32 v2, v2, v4, s33
	ds_write_b16_d16_hi v18, v2 offset:2176
	v_mul_f32_e32 v2, v7, v3
	v_cndmask_b32_e64 v3, v179, -v178, s[18:19]
	v_mul_f32_e32 v3, v3, v75
	v_mul_f32_e32 v3, 0x3fb8aa3b, v3
	v_exp_f32_e32 v3, v3
	v_bfe_u32 v4, v2, 16, 1
	v_add3_u32 v2, v2, v4, s33
	ds_write_b16_d16_hi v18, v2 offset:2448
	v_mul_f32_e32 v2, v8, v3
	v_cndmask_b32_e64 v3, v179, -v178, s[20:21]
	v_mul_f32_e32 v3, v3, v76
	v_mul_f32_e32 v3, 0x3fb8aa3b, v3
	v_bfe_u32 v4, v2, 16, 1
	v_exp_f32_e32 v3, v3
	v_add3_u32 v2, v2, v4, s33
	v_cndmask_b32_e64 v4, v179, -v178, s[22:23]
	v_mul_f32_e32 v4, v4, v78
	v_mul_f32_e32 v4, 0x3fb8aa3b, v4
	v_exp_f32_e32 v4, v4
	ds_write_b16_d16_hi v18, v2 offset:2720
	v_mul_f32_e32 v2, v9, v3
	v_bfe_u32 v3, v2, 16, 1
	v_add3_u32 v2, v2, v3, s33
	v_add_u32_e32 v3, v66, v77
	ds_write_b16_d16_hi v3, v2
	v_mul_f32_e32 v2, v10, v4
	v_cndmask_b32_e64 v4, v179, -v178, s[24:25]
	v_mul_f32_e32 v4, v4, v80
	v_mul_f32_e32 v4, 0x3fb8aa3b, v4
	v_exp_f32_e32 v4, v4
	v_bfe_u32 v3, v2, 16, 1
	v_add3_u32 v2, v2, v3, s33
	v_add_u32_e32 v3, v66, v79
	ds_write_b16_d16_hi v3, v2
	v_mul_f32_e32 v2, v11, v4
	v_cndmask_b32_e64 v4, v179, -v178, s[26:27]
	v_mul_f32_e32 v4, v4, v82
	v_mul_f32_e32 v4, 0x3fb8aa3b, v4
	v_exp_f32_e32 v4, v4
	v_bfe_u32 v3, v2, 16, 1
	v_add3_u32 v2, v2, v3, s33
	v_add_u32_e32 v3, v66, v81
	ds_write_b16_d16_hi v3, v2
	v_mul_f32_e32 v2, v12, v4
	v_cndmask_b32_e64 v4, v179, -v178, s[28:29]
	v_mul_f32_e32 v4, v4, v84
	v_mul_f32_e32 v4, 0x3fb8aa3b, v4
	v_exp_f32_e32 v4, v4
	v_bfe_u32 v3, v2, 16, 1
	v_add3_u32 v2, v2, v3, s33
	v_add_u32_e32 v3, v66, v83
	ds_write_b16_d16_hi v3, v2
	v_mul_f32_e32 v2, v13, v4
	v_cndmask_b32_e64 v4, v179, -v178, s[30:31]
	v_mul_f32_e32 v4, v4, v86
	v_mul_f32_e32 v4, 0x3fb8aa3b, v4
	v_exp_f32_e32 v4, v4
	v_bfe_u32 v3, v2, 16, 1
	v_add3_u32 v2, v2, v3, s33
	v_add_u32_e32 v3, v66, v85
	ds_write_b16_d16_hi v3, v2
	v_mul_f32_e32 v2, v14, v4
	v_cndmask_b32_e64 v4, v179, -v178, s[34:35]
	v_mul_f32_e32 v4, v4, v88
	v_mul_f32_e32 v4, 0x3fb8aa3b, v4
	v_exp_f32_e32 v4, v4
	v_bfe_u32 v3, v2, 16, 1
	v_add3_u32 v2, v2, v3, s33
	v_add_u32_e32 v3, v66, v87
	ds_write_b16_d16_hi v3, v2
	v_mul_f32_e32 v2, v15, v4
	v_cndmask_b32_e64 v4, v179, -v178, s[36:37]
	v_mul_f32_e32 v4, v4, v90
	v_mul_f32_e32 v4, 0x3fb8aa3b, v4
	v_exp_f32_e32 v4, v4
	v_bfe_u32 v3, v2, 16, 1
	v_add3_u32 v2, v2, v3, s33
	v_add_u32_e32 v3, v66, v89
	ds_write_b16_d16_hi v3, v2
	v_mul_f32_e32 v2, v16, v4
	v_cndmask_b32_e64 v4, v179, -v178, s[38:39]
	v_mul_f32_e32 v4, v4, v92
	v_mul_f32_e32 v4, 0x3fb8aa3b, v4
	v_exp_f32_e32 v4, v4
	v_bfe_u32 v3, v2, 16, 1
	v_add3_u32 v2, v2, v3, s33
	v_add_u32_e32 v3, v66, v91
	ds_write_b16_d16_hi v3, v2
	v_mul_f32_e32 v2, v17, v4
	v_bfe_u32 v3, v2, 16, 1
	v_add3_u32 v2, v2, v3, s33
	v_add_u32_e32 v3, v66, v93
	ds_write_b16_d16_hi v3, v2
	ds_read_b128 v[2:5], v163
	ds_read_b128 v[6:9], v30 offset:18432
	ds_read_b128 v[18:21], v163 offset:32
	ds_read_b128 v[22:25], v30 offset:18464
	s_waitcnt lgkmcnt(2)
; #define LAS __attribute__((address_space(3)))
; __device__ __forceinline__ unsigned f2bf(float f) { unsigned u = __builtin_bit_cast(unsigned, f); return (u + 0x7fffu + ((u >> 16) & 1u)) >> 16; }
; __device__ __forceinline__ int crow16(int r, int hi) { return (r & 3) + 8 * (r >> 2) + 4 * hi; }
; __device__ __forceinline__ void ret_out_unit(int unit, const bf16* RQ, const bf16* RK, const bf16* RV, const bf16* RG, const float* decay_l, const float* RETC, bf16* MIX, lds_t* lds, int tid, int lane, int wave) {
;     ...
;     for (int tt = 0; tt < 2; ++tt) { const int tile = wave * 2 + tt, it = tile >> 2, jt = tile & 3; f32x16 acc = {};
;         mma32<4>(acc, Qs + 32 * it * RT_LDD, RT_LDD, Ks + 32 * jt * RT_LDD, RT_LDD, lane);
;         const int j = 32 * jt + (lane & 31);
; #pragma unroll
;         for (int r = 0; r < 16; ++r) { const int i = 32 * it + crow16(r, lane >> 5); const float dd = (float)(i - j); const float w = acc[r] * __expf(dd >= 0.f ? lgf * dd : -lgb * dd);
;             *(LAS unsigned short*)(Ws + i * RT_LDK + j * 2) = (unsigned short)f2bf(w); } }
;     __syncthreads();
	v_mfma_f32_32x32x16_bf16 v[2:17], v[2:5], v[6:9], 0
	v_readlane_b32 s0, v255, 56
	v_readlane_b32 s1, v255, 57
	s_waitcnt lgkmcnt(0)
	v_mfma_f32_32x32x16_bf16 v[2:17], v[18:21], v[22:25], v[2:17]
	ds_read_b128 v[18:21], v163 offset:64
	ds_read_b128 v[22:25], v30 offset:18496
	ds_read_b128 v[26:29], v163 offset:96
	ds_read_b128 v[30:33], v30 offset:18528
	s_waitcnt lgkmcnt(2)
	v_mfma_f32_32x32x16_bf16 v[2:17], v[18:21], v[22:25], v[2:17]
	v_cndmask_b32_e64 v18, v179, -v178, s[40:41]
	v_mul_f32_e32 v18, v18, v95
	v_mul_f32_e32 v18, 0x3fb8aa3b, v18
	v_exp_f32_e32 v18, v18
	v_cndmask_b32_e64 v19, v179, -v178, s[42:43]
	v_mul_f32_e32 v19, v19, v96
	v_mul_f32_e32 v19, 0x3fb8aa3b, v19
	s_waitcnt lgkmcnt(0)
	v_mfma_f32_32x32x16_bf16 v[2:17], v[26:29], v[30:33], v[2:17]
	v_exp_f32_e32 v19, v19
	s_nop 10
	v_mul_f32_e32 v2, v18, v2
	v_bfe_u32 v18, v2, 16, 1
	v_add3_u32 v2, v2, v18, s33
	v_add_u32_e32 v18, v94, v68
	ds_write_b16_d16_hi v18, v2
	v_mul_f32_e32 v2, v19, v3
	v_cndmask_b32_e64 v3, v179, -v178, s[44:45]
	v_mul_f32_e32 v3, v3, v97
	v_mul_f32_e32 v3, 0x3fb8aa3b, v3
	v_exp_f32_e32 v3, v3
	v_bfe_u32 v19, v2, 16, 1
	v_add3_u32 v2, v2, v19, s33
	ds_write_b16_d16_hi v18, v2 offset:272
	v_mul_f32_e32 v2, v3, v4
	v_cndmask_b32_e64 v3, v179, -v178, s[46:47]
	v_mul_f32_e32 v3, v3, v98
	v_mul_f32_e32 v3, 0x3fb8aa3b, v3
	v_exp_f32_e32 v3, v3
	v_bfe_u32 v4, v2, 16, 1
	v_add3_u32 v2, v2, v4, s33
	ds_write_b16_d16_hi v18, v2 offset:544
	v_mul_f32_e32 v2, v3, v5
	v_cndmask_b32_e64 v4, v179, -v178, s[48:49]
	v_bfe_u32 v3, v2, 16, 1
	v_mul_f32_e32 v4, v4, v99
	v_mul_f32_e32 v4, 0x3fb8aa3b, v4
	v_add3_u32 v2, v2, v3, s33
	v_add_u32_e32 v3, v94, v72
	v_exp_f32_e32 v4, v4
	ds_write_b16_d16_hi v3, v2
	v_cndmask_b32_e64 v3, v179, -v178, s[50:51]
	v_mul_f32_e32 v3, v3, v100
	v_mul_f32_e32 v3, 0x3fb8aa3b, v3
	v_exp_f32_e32 v3, v3
	v_mul_f32_e32 v2, v4, v6
	v_bfe_u32 v4, v2, 16, 1
	v_add3_u32 v2, v2, v4, s33
	ds_write_b16_d16_hi v18, v2 offset:2176
	v_mul_f32_e32 v2, v3, v7
	v_cndmask_b32_e64 v3, v179, -v178, s[52:53]
	v_mul_f32_e32 v3, v3, v101
	v_mul_f32_e32 v3, 0x3fb8aa3b, v3
	v_exp_f32_e32 v3, v3
	v_bfe_u32 v4, v2, 16, 1
	v_add3_u32 v2, v2, v4, s33
	ds_write_b16_d16_hi v18, v2 offset:2448
	v_mul_f32_e32 v2, v3, v8
	v_cndmask_b32_e64 v3, v179, -v178, s[54:55]
	v_mul_f32_e32 v3, v3, v102
	v_mul_f32_e32 v3, 0x3fb8aa3b, v3
	v_bfe_u32 v4, v2, 16, 1
	v_exp_f32_e32 v3, v3
	v_add3_u32 v2, v2, v4, s33
	v_cndmask_b32_e64 v4, v179, -v178, s[56:57]
	v_mul_f32_e32 v4, v4, v103
	v_mul_f32_e32 v4, 0x3fb8aa3b, v4
	v_exp_f32_e32 v4, v4
	ds_write_b16_d16_hi v18, v2 offset:2720
	v_mul_f32_e32 v2, v3, v9
	v_bfe_u32 v3, v2, 16, 1
	v_add3_u32 v2, v2, v3, s33
	v_add_u32_e32 v3, v94, v77
	ds_write_b16_d16_hi v3, v2
	v_mul_f32_e32 v2, v4, v10
	v_cndmask_b32_e64 v4, v179, -v178, s[58:59]
	v_mul_f32_e32 v4, v4, v104
	v_mul_f32_e32 v4, 0x3fb8aa3b, v4
	v_exp_f32_e32 v4, v4
	v_bfe_u32 v3, v2, 16, 1
	v_add3_u32 v2, v2, v3, s33
	v_add_u32_e32 v3, v94, v79
	ds_write_b16_d16_hi v3, v2
	v_mul_f32_e32 v2, v4, v11
	v_cndmask_b32_e64 v4, v179, -v178, s[60:61]
	v_mul_f32_e32 v4, v4, v105
	v_mul_f32_e32 v4, 0x3fb8aa3b, v4
	v_exp_f32_e32 v4, v4
	v_bfe_u32 v3, v2, 16, 1
	v_add3_u32 v2, v2, v3, s33
	v_add_u32_e32 v3, v94, v81
	ds_write_b16_d16_hi v3, v2
	v_mul_f32_e32 v2, v4, v12
	v_cndmask_b32_e64 v4, v179, -v178, s[14:15]
	v_mul_f32_e32 v4, v4, v106
	v_mul_f32_e32 v4, 0x3fb8aa3b, v4
	v_exp_f32_e32 v4, v4
	v_bfe_u32 v3, v2, 16, 1
	v_add3_u32 v2, v2, v3, s33
	v_add_u32_e32 v3, v94, v83
	ds_write_b16_d16_hi v3, v2
	v_mul_f32_e32 v2, v4, v13
	v_cndmask_b32_e64 v4, v179, -v178, s[2:3]
	v_mul_f32_e32 v4, v4, v107
	v_mul_f32_e32 v4, 0x3fb8aa3b, v4
	v_exp_f32_e32 v4, v4
	v_bfe_u32 v3, v2, 16, 1
	v_add3_u32 v2, v2, v3, s33
	v_add_u32_e32 v3, v94, v85
	ds_write_b16_d16_hi v3, v2
	v_mul_f32_e32 v2, v4, v14
	v_cndmask_b32_e64 v4, v179, -v178, s[4:5]
	v_mul_f32_e32 v4, v4, v108
	v_mul_f32_e32 v4, 0x3fb8aa3b, v4
	v_exp_f32_e32 v4, v4
	v_bfe_u32 v3, v2, 16, 1
	v_add3_u32 v2, v2, v3, s33
	v_add_u32_e32 v3, v94, v87
	ds_write_b16_d16_hi v3, v2
	v_mul_f32_e32 v2, v4, v15
	v_cndmask_b32_e64 v4, v179, -v178, s[68:69]
	v_mul_f32_e32 v4, v4, v109
	v_mul_f32_e32 v4, 0x3fb8aa3b, v4
	v_exp_f32_e32 v4, v4
	v_bfe_u32 v3, v2, 16, 1
	v_add3_u32 v2, v2, v3, s33
	v_add_u32_e32 v3, v94, v89
	ds_write_b16_d16_hi v3, v2
	v_mul_f32_e32 v2, v4, v16
	v_cndmask_b32_e64 v4, v179, -v178, s[70:71]
	v_mul_f32_e32 v4, v4, v110
	v_mul_f32_e32 v4, 0x3fb8aa3b, v4
	v_exp_f32_e32 v4, v4
	v_bfe_u32 v3, v2, 16, 1
	v_add3_u32 v2, v2, v3, s33
	v_add_u32_e32 v3, v94, v91
	ds_write_b16_d16_hi v3, v2
	v_mul_f32_e32 v2, v4, v17
	v_bfe_u32 v3, v2, 16, 1
	v_add3_u32 v2, v2, v3, s33
	v_add_u32_e32 v3, v94, v93
	ds_write_b16_d16_hi v3, v2
	s_waitcnt lgkmcnt(0)
	s_barrier
; #define LAS __attribute__((address_space(3)))
; __device__ __forceinline__ int crow16(int r, int hi) { return (r & 3) + 8 * (r >> 2) + 4 * hi; }
; __device__ __forceinline__ void ret_out_unit(int unit, const bf16* RQ, const bf16* RK, const bf16* RV, const bf16* RG, const float* decay_l, const float* RETC, bf16* MIX, lds_t* lds, int tid, int lane, int wave) {
;     ...
;     f32x16 o;
;     { const int it = wave >> 1, vt = wave & 1; f32x16 a1 = {}, a2 = {}, a3 = {};
;         mma32<8>(a1, Ws + 32 * it * RT_LDK, RT_LDK, Vt + 32 * vt * RT_LDK, RT_LDK, lane);
;         mma32<4>(a2, Qs + 32 * it * RT_LDD, RT_LDD, Sft + 32 * vt * RT_LDD, RT_LDD, lane);
;         mma32<4>(a3, Qs + 32 * it * RT_LDD, RT_LDD, Sbt + 32 * vt * RT_LDD, RT_LDD, lane);
; #pragma unroll
;         for (int r = 0; r < 16; ++r) { const int i = 32 * it + crow16(r, lane >> 5); o[r] = a1[r] + __expf(lgf * (float)(i + 1)) * a2[r] + __expf(lgb * (float)(128 - i)) * a3[r]; } }
;     __syncthreads();
;     { const int it = wave >> 1, vt = wave & 1; LAS float* Os = (LAS float*)Ws;
; #pragma unroll
;         for (int r = 0; r < 16; ++r) Os[(32 * it + crow16(r, lane >> 5)) * 65 + 32 * vt + (lane & 31)] = o[r]; }
;     __syncthreads();
	ds_read_b128 v[2:5], v164
	ds_read_b128 v[6:9], v165 offset:36864
	ds_read_b128 v[18:21], v164 offset:32
	ds_read_b128 v[22:25], v165 offset:36896
	s_waitcnt lgkmcnt(2)
	v_mfma_f32_32x32x16_bf16 v[2:17], v[2:5], v[6:9], 0
	s_waitcnt lgkmcnt(0)
	v_mfma_f32_32x32x16_bf16 v[2:17], v[18:21], v[22:25], v[2:17]
	ds_read_b128 v[18:21], v164 offset:64
	ds_read_b128 v[22:25], v165 offset:36928
	ds_read_b128 v[26:29], v164 offset:96
	ds_read_b128 v[30:33], v165 offset:36960
	s_waitcnt lgkmcnt(2)
	v_mfma_f32_32x32x16_bf16 v[2:17], v[18:21], v[22:25], v[2:17]
	s_waitcnt lgkmcnt(0)
	v_mfma_f32_32x32x16_bf16 v[2:17], v[26:29], v[30:33], v[2:17]
	ds_read_b128 v[18:21], v164 offset:128
	ds_read_b128 v[22:25], v165 offset:36992
	ds_read_b128 v[26:29], v164 offset:160
	ds_read_b128 v[30:33], v165 offset:37024
	s_waitcnt lgkmcnt(2)
	v_mfma_f32_32x32x16_bf16 v[2:17], v[18:21], v[22:25], v[2:17]
	s_waitcnt lgkmcnt(0)
	v_mfma_f32_32x32x16_bf16 v[2:17], v[26:29], v[30:33], v[2:17]
	ds_read_b128 v[18:21], v164 offset:192
	ds_read_b128 v[22:25], v165 offset:37056
	ds_read_b128 v[26:29], v164 offset:224
	ds_read_b128 v[30:33], v165 offset:37088
	s_waitcnt lgkmcnt(2)
	v_mfma_f32_32x32x16_bf16 v[2:17], v[18:21], v[22:25], v[2:17]
	ds_read_b128 v[34:37], v163
	ds_read_b128 v[18:21], v166 offset:54272
	ds_read_b128 v[180:183], v163 offset:32
	ds_read_b128 v[38:41], v166 offset:54304
	s_waitcnt lgkmcnt(4)
	v_mfma_f32_32x32x16_bf16 v[2:17], v[26:29], v[30:33], v[2:17]
	s_waitcnt lgkmcnt(2)
	v_mfma_f32_32x32x16_bf16 v[18:33], v[34:37], v[18:21], 0
	s_waitcnt lgkmcnt(0)
	v_mfma_f32_32x32x16_bf16 v[18:33], v[180:183], v[38:41], v[18:33]
	ds_read_b128 v[184:187], v163 offset:64
	ds_read_b128 v[38:41], v166 offset:54336
	ds_read_b128 v[188:191], v163 offset:96
	ds_read_b128 v[42:45], v166 offset:54368
	s_waitcnt lgkmcnt(2)
	v_mfma_f32_32x32x16_bf16 v[18:33], v[184:187], v[38:41], v[18:33]
	ds_read_b128 v[38:41], v166 offset:63488
	ds_read_b128 v[192:195], v166 offset:63520
	s_waitcnt lgkmcnt(2)
	v_mfma_f32_32x32x16_bf16 v[18:33], v[188:191], v[42:45], v[18:33]
	s_waitcnt lgkmcnt(1)
	v_mfma_f32_32x32x16_bf16 v[34:49], v[34:37], v[38:41], 0
	s_waitcnt lgkmcnt(0)
	v_mfma_f32_32x32x16_bf16 v[34:49], v[180:183], v[192:195], v[34:49]
	ds_read_b128 v[180:183], v166 offset:63552
	ds_read_b128 v[192:195], v166 offset:63584
	s_waitcnt lgkmcnt(0)
	s_barrier
	v_mfma_f32_32x32x16_bf16 v[34:49], v[184:187], v[180:183], v[34:49]
	v_mul_f32_e32 v180, v179, v111
	v_mul_f32_e32 v180, 0x3fb8aa3b, v180
	v_mul_f32_e32 v181, v178, v112
	v_mul_f32_e32 v182, v179, v113
	v_exp_f32_e32 v180, v180
	v_mul_f32_e32 v181, 0x3fb8aa3b, v181
	v_mul_f32_e32 v182, 0x3fb8aa3b, v182
	v_mfma_f32_32x32x16_bf16 v[34:49], v[188:191], v[192:195], v[34:49]
	v_exp_f32_e32 v181, v181
	v_exp_f32_e32 v182, v182
	v_fma_f32 v2, v180, v18, v2
	v_mul_f32_e32 v18, v179, v131
	v_mul_f32_e32 v18, 0x3fb8aa3b, v18
	v_fma_f32 v3, v182, v19, v3
	v_mul_f32_e32 v19, v178, v132
	s_nop 4
	v_fmac_f32_e32 v2, v181, v34
	v_mul_f32_e32 v34, v179, v133
	v_exp_f32_e32 v18, v18
	v_mul_f32_e32 v19, 0x3fb8aa3b, v19
	v_mul_f32_e32 v34, 0x3fb8aa3b, v34
	v_exp_f32_e32 v19, v19
	v_exp_f32_e32 v34, v34
	v_fma_f32 v4, v18, v20, v4
	v_mul_f32_e32 v18, v179, v135
	v_mul_f32_e32 v20, v179, v137
	v_fmac_f32_e32 v4, v19, v36
	v_fma_f32 v5, v34, v21, v5
	v_mul_f32_e32 v18, 0x3fb8aa3b, v18
	v_mul_f32_e32 v19, v178, v136
	v_mul_f32_e32 v20, 0x3fb8aa3b, v20
	v_mul_f32_e32 v21, v178, v138
	v_exp_f32_e32 v18, v18
	v_mul_f32_e32 v19, 0x3fb8aa3b, v19
	v_exp_f32_e32 v20, v20
	v_mul_f32_e32 v21, 0x3fb8aa3b, v21
	v_exp_f32_e32 v19, v19
	v_exp_f32_e32 v21, v21
	v_fma_f32 v6, v18, v22, v6
	v_fma_f32 v7, v20, v23, v7
	v_mul_f32_e32 v18, v179, v139
	v_mul_f32_e32 v20, v179, v141
	v_fmac_f32_e32 v6, v19, v38
	v_fmac_f32_e32 v7, v21, v39
	v_mul_f32_e32 v18, 0x3fb8aa3b, v18
	v_mul_f32_e32 v19, v178, v140
	v_mul_f32_e32 v20, 0x3fb8aa3b, v20
	v_mul_f32_e32 v21, v178, v142
	v_exp_f32_e32 v18, v18
	v_mul_f32_e32 v19, 0x3fb8aa3b, v19
	v_exp_f32_e32 v20, v20
	v_mul_f32_e32 v21, 0x3fb8aa3b, v21
	v_exp_f32_e32 v19, v19
	v_exp_f32_e32 v21, v21
	v_fma_f32 v8, v18, v24, v8
	v_fma_f32 v9, v20, v25, v9
	v_mul_f32_e32 v18, v179, v143
	v_mul_f32_e32 v20, v179, v145
	v_fmac_f32_e32 v8, v19, v40
	v_fmac_f32_e32 v9, v21, v41
	v_mul_f32_e32 v18, 0x3fb8aa3b, v18
	v_mul_f32_e32 v19, v178, v144
	v_mul_f32_e32 v20, 0x3fb8aa3b, v20
	v_mul_f32_e32 v21, v178, v146
	v_exp_f32_e32 v18, v18
	v_mul_f32_e32 v19, 0x3fb8aa3b, v19
	v_exp_f32_e32 v20, v20
	v_mul_f32_e32 v21, 0x3fb8aa3b, v21
	v_exp_f32_e32 v19, v19
	v_exp_f32_e32 v21, v21
	v_fma_f32 v10, v18, v26, v10
	v_fma_f32 v11, v20, v27, v11
	v_mul_f32_e32 v18, v179, v147
	v_mul_f32_e32 v20, v179, v149
	v_fmac_f32_e32 v10, v19, v42
	v_fmac_f32_e32 v11, v21, v43
	v_mul_f32_e32 v18, 0x3fb8aa3b, v18
	v_mul_f32_e32 v19, v178, v148
	v_mul_f32_e32 v20, 0x3fb8aa3b, v20
	v_mul_f32_e32 v21, v178, v150
	v_exp_f32_e32 v18, v18
	v_mul_f32_e32 v19, 0x3fb8aa3b, v19
	v_exp_f32_e32 v20, v20
	v_mul_f32_e32 v21, 0x3fb8aa3b, v21
	v_exp_f32_e32 v19, v19
	v_exp_f32_e32 v21, v21
	v_fma_f32 v12, v18, v28, v12
	v_fma_f32 v13, v20, v29, v13
	v_mul_f32_e32 v18, v179, v151
	v_mul_f32_e32 v20, v179, v153
	v_mul_f32_e32 v183, v178, v130
	v_fmac_f32_e32 v12, v19, v44
	v_fmac_f32_e32 v13, v21, v45
	v_mul_f32_e32 v18, 0x3fb8aa3b, v18
	v_mul_f32_e32 v19, v178, v152
	v_mul_f32_e32 v20, 0x3fb8aa3b, v20
	v_mul_f32_e32 v21, v178, v154
	v_mul_f32_e32 v183, 0x3fb8aa3b, v183
	v_exp_f32_e32 v18, v18
	v_mul_f32_e32 v19, 0x3fb8aa3b, v19
	v_exp_f32_e32 v20, v20
	v_mul_f32_e32 v21, 0x3fb8aa3b, v21
	v_exp_f32_e32 v183, v183
	v_exp_f32_e32 v19, v19
	v_exp_f32_e32 v21, v21
	v_fma_f32 v14, v18, v30, v14
	v_fma_f32 v15, v20, v31, v15
	v_mul_f32_e32 v18, v179, v155
	v_mul_f32_e32 v20, v179, v157
	v_fmac_f32_e32 v3, v183, v35
	v_mul_f32_e32 v35, v178, v134
	v_fmac_f32_e32 v14, v19, v46
	v_fmac_f32_e32 v15, v21, v47
	v_mul_f32_e32 v18, 0x3fb8aa3b, v18
	v_mul_f32_e32 v19, v178, v156
	v_mul_f32_e32 v20, 0x3fb8aa3b, v20
	v_mul_f32_e32 v21, v178, v158
	v_mul_f32_e32 v35, 0x3fb8aa3b, v35
	v_exp_f32_e32 v18, v18
	v_mul_f32_e32 v19, 0x3fb8aa3b, v19
	v_exp_f32_e32 v20, v20
	v_mul_f32_e32 v21, 0x3fb8aa3b, v21
	v_exp_f32_e32 v35, v35
	v_exp_f32_e32 v19, v19
	v_exp_f32_e32 v21, v21
	v_fma_f32 v16, v18, v32, v16
	v_fmac_f32_e32 v17, v20, v33
	v_fmac_f32_e32 v5, v35, v37
	v_fmac_f32_e32 v16, v19, v48
	v_fmac_f32_e32 v17, v21, v49
	ds_write2_b32 v167, v2, v3 offset1:65
	ds_write_b32 v167, v4 offset:520
	ds_write_b32 v168, v5
	v_add_u32_e32 v2, 0x800, v167
	ds_write2_b32 v2, v6, v7 offset0:8 offset1:73
	ds_write_b32 v167, v8 offset:2600
	ds_write_b32 v169, v9
	ds_write_b32 v170, v10
	ds_write_b32 v171, v11
	ds_write_b32 v172, v12
	ds_write_b32 v173, v13
	ds_write_b32 v174, v14
	ds_write_b32 v175, v15
	ds_write_b32 v176, v16
	ds_write_b32 v177, v17
	s_waitcnt lgkmcnt(0)
	s_barrier
; #define LAS __attribute__((address_space(3)))
; __device__ __forceinline__ unsigned pk2(float lo, float hi) { return f2bf(lo) | (f2bf(hi) << 16); }
; __device__ __forceinline__ void ret_out_unit(int unit, const bf16* RQ, const bf16* RK, const bf16* RV, const bf16* RG, const float* decay_l, const float* RETC, bf16* MIX, lds_t* lds, int tid, int lane, int wave) {
;     ...
;     { const int i = tid >> 2, c0 = (tid & 3) * 16; const LAS float* Os = (const LAS float*)Ws + i * 65 + c0; float vals[16]; float ss = 0.f;
; #pragma unroll
;         for (int e = 0; e < 16; ++e) { vals[e] = Os[e]; ss += vals[e] * vals[e]; }
;         ss += __shfl_xor(ss, 1); ss += __shfl_xor(ss, 2);
;         const float rs = rsqrtf(ss * (1.0f / 64.0f) + EPSN);
;         bf16* dst = MIX + (size_t)(m0 + i) * DM + h * 64 + c0;
; #pragma unroll
;         for (int q = 0; q < 2; ++q) { const v4u gw = gpre[q]; v4u ow;
; #pragma unroll
;             for (int e = 0; e < 4; ++e) ow[e] = pk2(vals[q * 8 + 2 * e] * rs * bflo(gw[e]), vals[q * 8 + 2 * e + 1] * rs * bfhi(gw[e]));
;             *(v4u*)(dst + 8 * q) = ow; } }
;     __syncthreads();
	ds_read2_b32 v[2:3], v159 offset0:12 offset1:13
	ds_read2_b32 v[4:5], v159 offset0:14 offset1:15
	ds_read2_b32 v[16:17], v159 offset0:10 offset1:11
	ds_read2_b32 v[10:11], v159 offset0:2 offset1:3
	ds_read2_b32 v[8:9], v159 offset0:6 offset1:7
	ds_read2_b32 v[22:23], v159 offset0:4 offset1:5
	ds_read2_b32 v[14:15], v159 offset1:1
	ds_read2_b32 v[28:29], v159 offset0:8 offset1:9
	s_waitcnt lgkmcnt(4)
	v_pk_mul_f32 v[24:25], v[10:11], v[10:11]
	s_waitcnt lgkmcnt(3)
	v_pk_mul_f32 v[32:33], v[8:9], v[8:9]
	s_waitcnt lgkmcnt(2)
	v_pk_mul_f32 v[34:35], v[22:23], v[22:23]
	s_waitcnt lgkmcnt(1)
	v_pk_mul_f32 v[26:27], v[14:15], v[14:15]
	s_waitcnt lgkmcnt(0)
	v_pk_mul_f32 v[36:37], v[28:29], v[28:29]
	v_add_f32_e32 v26, v26, v27
	v_add_f32_e32 v24, v26, v24
	v_add_f32_e32 v24, v24, v25
	v_add_f32_e32 v24, v24, v34
	v_add_f32_e32 v24, v24, v35
	v_add_f32_e32 v24, v24, v32
	v_add_f32_e32 v24, v24, v33
	v_add_f32_e32 v24, v24, v36
	v_pk_mul_f32 v[38:39], v[16:17], v[16:17]
	v_add_f32_e32 v24, v24, v37
	v_add_f32_e32 v24, v24, v38
	v_pk_mul_f32 v[20:21], v[2:3], v[2:3]
	v_and_b32_e32 v7, 64, v218
	v_add_f32_e32 v24, v24, v39
	v_xor_b32_e32 v6, 1, v218
	v_add_u32_e32 v7, 64, v7
	v_add_f32_e32 v20, v24, v20
	v_pk_mul_f32 v[18:19], v[4:5], v[4:5]
	v_cmp_lt_i32_e32 vcc, v6, v7
	v_add_f32_e32 v20, v20, v21
	v_add_f32_e32 v18, v20, v18
	v_cndmask_b32_e32 v6, v218, v6, vcc
	v_lshlrev_b32_e32 v40, 2, v6
	v_add_f32_e32 v20, v18, v19
	ds_bpermute_b32 v24, v40, v20
	v_xor_b32_e32 v6, 2, v218
	v_cmp_lt_i32_e32 vcc, v6, v7
	v_mov_b32_e32 v12, v14
	v_mov_b32_e32 v13, v10
	v_cndmask_b32_e32 v6, v218, v6, vcc
	v_lshlrev_b32_e32 v41, 2, v6
	s_waitcnt lgkmcnt(0)
	v_add_f32_e32 v25, v20, v24
	ds_bpermute_b32 v26, v41, v25
	v_lshlrev_b64 v[6:7], 11, v[60:61]
	v_lshl_add_u64 v[6:7], s[0:1], 0, v[6:7]
	s_mov_b32 s0, 0x800000
	v_mov_b32_e32 v10, v15
	s_waitcnt lgkmcnt(0)
	v_add_f32_e32 v25, v25, v26
	v_fmamk_f32 v25, v25, 0x3c800000, v213
	v_mul_f32_e32 v26, 0x4b800000, v25
	v_cmp_gt_f32_e32 vcc, s0, v25
	v_mov_b32_e32 v19, v8
	v_mov_b32_e32 v8, v23
	v_cndmask_b32_e32 v25, v25, v26, vcc
	v_rsq_f32_e32 v26, v25
	s_waitcnt vmcnt(0)
	v_lshlrev_b32_e32 v15, 16, v55
	v_lshlrev_b32_e32 v14, 16, v54
	v_and_b32_e32 v31, 0xffff0000, v55
	v_mul_f32_e32 v27, 0x45800000, v26
	v_cndmask_b32_e32 v26, v26, v27, vcc
	v_and_b32_e32 v30, 0xffff0000, v54
	v_mov_b32_e32 v18, v22
	v_and_b32_e32 v23, 0xffff0000, v57
	v_and_b32_e32 v22, 0xffff0000, v56
	v_pk_mul_f32 v[12:13], v[12:13], v[26:27] op_sel_hi:[1,0]
	v_pk_mul_f32 v[10:11], v[10:11], v[26:27] op_sel_hi:[1,0]
	v_pk_mul_f32 v[8:9], v[8:9], v[26:27] op_sel_hi:[1,0]
	v_lshlrev_b32_e32 v21, 16, v57
	v_lshlrev_b32_e32 v20, 16, v56
	v_pk_mul_f32 v[12:13], v[12:13], v[14:15]
	v_pk_mul_f32 v[10:11], v[10:11], v[30:31]
	v_pk_mul_f32 v[14:15], v[18:19], v[26:27] op_sel_hi:[1,0]
	v_pk_mul_f32 v[8:9], v[8:9], v[22:23]
	v_pk_mul_f32 v[14:15], v[14:15], v[20:21]
	v_bfe_u32 v18, v9, 16, 1
	v_bfe_u32 v19, v8, 16, 1
	v_bfe_u32 v20, v11, 16, 1
	v_bfe_u32 v21, v10, 16, 1
	v_add3_u32 v21, v10, v21, s33
	v_add3_u32 v20, v11, v20, s33
	v_add3_u32 v8, v8, v19, s33
	v_add3_u32 v9, v9, v18, s33
	v_bfe_u32 v10, v12, 16, 1
	v_bfe_u32 v11, v13, 16, 1
	v_bfe_u32 v18, v14, 16, 1
	v_bfe_u32 v19, v15, 16, 1
	v_add3_u32 v15, v15, v19, s33
	v_add3_u32 v14, v14, v18, s33
	v_add3_u32 v11, v13, v11, s33
	v_add3_u32 v10, v12, v10, s33
	v_lshl_add_u64 v[6:7], v[6:7], 0, s[84:85]
	v_lshrrev_b32_e32 v12, 16, v10
	v_lshrrev_b32_e32 v13, 16, v11
	v_lshrrev_b32_e32 v10, 16, v14
	v_lshrrev_b32_e32 v11, 16, v15
	v_lshl_add_u64 v[6:7], v[6:7], 0, v[0:1]
	v_mov_b32_e32 v24, v28
	v_mov_b32_e32 v25, v16
	v_and_or_b32 v11, v9, s87, v11
	v_and_or_b32 v10, v8, s87, v10
	v_and_or_b32 v9, v20, s87, v13
	v_and_or_b32 v8, v21, s87, v12
	v_mov_b32_e32 v16, v29
	global_store_dwordx4 v[6:7], v[8:11], off
	v_and_b32_e32 v13, 0xffff0000, v51
	v_and_b32_e32 v12, 0xffff0000, v50
	v_pk_mul_f32 v[8:9], v[24:25], v[26:27] op_sel_hi:[1,0]
	v_lshlrev_b32_e32 v11, 16, v51
	v_lshlrev_b32_e32 v10, 16, v50
	v_pk_mul_f32 v[8:9], v[8:9], v[10:11]
	v_pk_mul_f32 v[10:11], v[16:17], v[26:27] op_sel_hi:[1,0]
	v_lshlrev_b32_e32 v15, 16, v53
	v_pk_mul_f32 v[10:11], v[10:11], v[12:13]
	v_mov_b32_e32 v13, v4
	v_mov_b32_e32 v4, v3
	v_mov_b32_e32 v12, v2
	v_pk_mul_f32 v[2:3], v[4:5], v[26:27] op_sel_hi:[1,0]
	v_and_b32_e32 v5, 0xffff0000, v53
	v_and_b32_e32 v4, 0xffff0000, v52
	v_pk_mul_f32 v[12:13], v[12:13], v[26:27] op_sel_hi:[1,0]
	v_lshlrev_b32_e32 v14, 16, v52
	v_pk_mul_f32 v[2:3], v[2:3], v[4:5]
	v_pk_mul_f32 v[12:13], v[12:13], v[14:15]
	v_bfe_u32 v4, v3, 16, 1
	v_bfe_u32 v5, v2, 16, 1
	v_bfe_u32 v14, v11, 16, 1
	v_bfe_u32 v15, v10, 16, 1
	v_add3_u32 v10, v10, v15, s33
	v_add3_u32 v11, v11, v14, s33
	v_add3_u32 v2, v2, v5, s33
	v_add3_u32 v3, v3, v4, s33
	v_bfe_u32 v4, v8, 16, 1
	v_bfe_u32 v5, v9, 16, 1
	v_bfe_u32 v14, v12, 16, 1
	v_bfe_u32 v15, v13, 16, 1
	v_add3_u32 v13, v13, v15, s33
	v_add3_u32 v12, v12, v14, s33
	v_add3_u32 v5, v9, v5, s33
	v_add3_u32 v4, v8, v4, s33
	v_lshrrev_b32_e32 v8, 16, v4
	v_lshrrev_b32_e32 v9, 16, v5
	v_lshrrev_b32_e32 v4, 16, v12
	v_lshrrev_b32_e32 v5, 16, v13
	v_and_or_b32 v5, v3, s87, v5
	v_and_or_b32 v4, v2, s87, v4
	v_and_or_b32 v3, v11, s87, v9
	v_and_or_b32 v2, v10, s87, v8
	global_store_dwordx4 v[6:7], v[2:5], off offset:16
	s_barrier
